# P2 new-state row copies run on the 64 CUs without a sample-conv unit (they waited at the barrier)
# speedup vs baseline: 1.1218x; 1.0013x over previous
; #define GAS __attribute__((address_space(1)))
; __device__ __forceinline__ float bf_lo(unsigned w) { return __uint_as_float(w << 16); }
; __device__ __forceinline__ float bf_hi(unsigned w) { return __uint_as_float(w & 0xffff0000u); }
; __device__ __forceinline__ void p2_states(Frame& F) {
;     const bf16_t* U = WSP(bf16_t, WS_U); const bf16_t* A = WSP(bf16_t, WS_A);
;     constexpr int R_PSP = NB * PSTATE, R_CSP = NB * CSTATE, R_S = DB * DS;
;     const unsigned ln = (unsigned)F.lane;
;     for (int i = F.vcu * NWAVES + F.wave; i < R_PSP + R_CSP + 2 * R_S; i += F.G * NWAVES) {
;         int r = i; const bf16_t* sb; float* dst;
;         if (r < R_PSP) { const int j = r % PSTATE, b = r / PSTATE; sb = U + (size_t)(b * SEQ + SEQ - PSTATE + j) * DPOOL; dst = F.out + O_PSP + (size_t)r * DPOOL; }
;         else if ((r -= R_PSP) < R_CSP) { const int j = r % CSTATE, b = r / CSTATE; sb = A + (size_t)(b * SEQ + SEQ - CSTATE + j) * DCONV; dst = F.out + O_CSP + (size_t)r * DCONV; }
;         else if ((r -= R_CSP) < R_S) { const int b = r >> 2, t = r & 3; sb = U + (size_t)(MP + r) * DPOOL; dst = F.out + O_PSS + (size_t)(b * PSTATE + PSTATE - DS + t) * DPOOL; }
;         else { r -= R_S; const int b = r >> 2, t = r & 3; sb = A + (size_t)(MP + r) * DCONV; dst = F.out + O_CSS + (size_t)(b * CSTATE + CSTATE - DS + t) * DCONV; }
;         f32x4 v[6];
; #pragma unroll
;         for (int k = 0; k < 6; ++k) { const u32x2 w = ldg<u32x2>(sb, (256u * k + 4u * ln) * 2u); v[k] = (f32x4){bf_lo(w.x), bf_hi(w.x), bf_lo(w.y), bf_hi(w.y)}; }
; #pragma unroll
;         for (int k = 0; k < 6; ++k) *(GAS f32x4*)((char*)dst + (256u * k + 4u * ln) * 4u) = v[k];
;     }
; }
; __device__ __forceinline__ void p2_mixers(LAS unsigned char* lds, const ConvW& cw) {
;     ...
;     { Frame F = make_frame(lds); p2_states(F); if ((int)gridDim.x != 256) states_copy_rows(F, F.vcu * NWAVES + F.wave, F.G * NWAVES); }
.LBB0_543:
	s_mov_b64 s[12:13], s[0:1]
	s_load_dwordx4 s[8:11], s[12:13], 0x28
	s_load_dwordx4 s[16:19], s[12:13], 0xa8
	s_ashr_i32 s7, s24, 6
	s_sub_i32 s6, s6, 0xc0
	s_cmp_lt_i32 s6, 0
	s_cbranch_scc1 .LBB0_558
	s_lshl_b32 s6, s6, 3
	v_and_b32_e32 v3, 63, v2
	s_add_i32 s29, s6, s7
	s_cmpk_gt_i32 s29, 0x4b3
	v_lshlrev_b32_e32 v2, 4, v3
	s_cbranch_scc1 .LBB0_558
	s_waitcnt lgkmcnt(0)
	s_add_u32 s34, s18, 0x2a00000
	s_addc_u32 s35, s19, 0
	s_add_u32 s36, s18, 0x5e00000
	s_addc_u32 s37, s19, 0
	s_add_u32 s6, s16, 0x9c4e000
	s_addc_u32 s7, s17, 0
	s_add_u32 s12, s16, 0x910e000
	s_addc_u32 s13, s17, 0
	s_add_u32 s18, s16, 0x905a000
	s_addc_u32 s19, s17, 0
	s_add_u32 s22, s16, 0x9000000
	v_mov_b32_e32 v5, 0
	s_addc_u32 s23, s17, 0
	s_bfe_u32 s47, s24, 0x20006
	v_lshlrev_b32_e32 v4, 3, v3
	v_mov_b32_e32 v3, v5
	s_add_i32 s46, s47, 26
	s_add_i32 s47, s47, 11
	s_mul_i32 s48, s29, 0xc00
	s_mov_b32 s49, 0x180000
	s_mov_b32 s25, 0
	s_mov_b32 s26, s29
	s_branch .LBB0_546
.LBB0_545:
	v_lshl_add_u64 v[6:7], s[38:39], 0, v[4:5]
	global_load_dwordx2 v[8:9], v[6:7], off
	global_load_dwordx2 v[12:13], v[6:7], off offset:512
	global_load_dwordx2 v[16:17], v[6:7], off offset:1024
	global_load_dwordx2 v[20:21], v[6:7], off offset:1536
	global_load_dwordx2 v[24:25], v[6:7], off offset:2048
	global_load_dwordx2 v[28:29], v[6:7], off offset:2560
	s_mul_i32 s24, s41, 0x1800
	s_mul_hi_u32 s27, s40, 0x1800
	s_mul_i32 s38, s40, 0x1800
	s_add_i32 s27, s27, s24
	s_add_u32 s38, s42, s38
	s_addc_u32 s39, s43, s27
	s_addk_i32 s26, 0x200
	s_add_i32 s48, s48, s49
	v_lshl_add_u64 v[30:31], s[38:39], 0, v[2:3]
	s_cmpk_lt_i32 s26, 0x4b4
	v_add_co_u32_e32 v32, vcc, 0x1000, v30
	s_waitcnt vmcnt(5)
	v_lshlrev_b32_e32 v6, 16, v8
	v_and_b32_e32 v7, 0xffff0000, v8
	v_lshlrev_b32_e32 v8, 16, v9
	v_and_b32_e32 v9, 0xffff0000, v9
	v_addc_co_u32_e32 v33, vcc, 0, v31, vcc
	s_waitcnt vmcnt(4)
	v_lshlrev_b32_e32 v10, 16, v12
	v_and_b32_e32 v11, 0xffff0000, v12
	v_lshlrev_b32_e32 v12, 16, v13
	v_and_b32_e32 v13, 0xffff0000, v13
	s_waitcnt vmcnt(3)
	v_lshlrev_b32_e32 v14, 16, v16
	v_and_b32_e32 v15, 0xffff0000, v16
	v_lshlrev_b32_e32 v16, 16, v17
	v_and_b32_e32 v17, 0xffff0000, v17
	s_waitcnt vmcnt(2)
	v_lshlrev_b32_e32 v18, 16, v20
	v_and_b32_e32 v19, 0xffff0000, v20
	v_lshlrev_b32_e32 v20, 16, v21
	v_and_b32_e32 v21, 0xffff0000, v21
	s_waitcnt vmcnt(1)
	v_lshlrev_b32_e32 v22, 16, v24
	v_and_b32_e32 v23, 0xffff0000, v24
	v_lshlrev_b32_e32 v24, 16, v25
	v_and_b32_e32 v25, 0xffff0000, v25
	s_waitcnt vmcnt(0)
	v_lshlrev_b32_e32 v26, 16, v28
	v_and_b32_e32 v27, 0xffff0000, v28
	v_lshlrev_b32_e32 v28, 16, v29
	v_and_b32_e32 v29, 0xffff0000, v29
	global_store_dwordx4 v[30:31], v[6:9], off
	global_store_dwordx4 v[30:31], v[10:13], off offset:1024
	global_store_dwordx4 v[30:31], v[14:17], off offset:2048
	global_store_dwordx4 v[30:31], v[18:21], off offset:3072
	global_store_dwordx4 v[32:33], v[22:25], off
	global_store_dwordx4 v[32:33], v[26:29], off offset:1024
	s_cbranch_scc0 .LBB0_558
